# GLA chunk prefix scans: DPP row_shr/row_bcast adds instead of six ds_bpermute round trips (gla1 and gla3)
# speedup vs baseline: 1.0120x; 1.0120x over previous
; DI float scan64(float x, int lane) {
; #pragma unroll
;     for (int off = 1; off < 64; off <<= 1) { const float y = __int_as_float(__builtin_amdgcn_ds_bpermute((lane - off) << 2, __float_as_int(x))); if (lane >= off) x += y; }
;     return x;
; }
; DI void phase_gla1(ArgsP a, int tb_, int l, char* shm, int vcu, int G) {
;     ...
; #pragma unroll
;             for (int i = 0; i < 8; ++i) { const int kd = wid * 8 + i, jj = dir ? 63 - lane : lane; const float x = scan64(LA[jj * 65 + kd], lane); LA[jj * 65 + kd] = x; }
;             __syncthreads();
.LBB0_1264:
	s_or_b64 exec, exec, s[44:45]
	s_waitcnt lgkmcnt(0)
	s_barrier
	ds_read2_b32 v[0:1], v59 offset0:2 offset1:3
	ds_read2_b32 v[2:3], v59 offset1:1
	v_add_u32_e32 v12, s49, v52
	v_lshlrev_b32_e32 v8, 16, v46
	v_and_b32_e32 v9, 0xffff0000, v46
	s_waitcnt lgkmcnt(0)
	v_add_f32_dpp v0, v0, v0 row_shr:1 row_mask:0xf bank_mask:0xf bound_ctrl:1
	v_add_f32_dpp v1, v1, v1 row_shr:1 row_mask:0xf bank_mask:0xf bound_ctrl:1
	v_add_f32_dpp v2, v2, v2 row_shr:1 row_mask:0xf bank_mask:0xf bound_ctrl:1
	v_add_f32_dpp v3, v3, v3 row_shr:1 row_mask:0xf bank_mask:0xf bound_ctrl:1
	v_add_f32_dpp v0, v0, v0 row_shr:2 row_mask:0xf bank_mask:0xf bound_ctrl:1
	v_add_f32_dpp v1, v1, v1 row_shr:2 row_mask:0xf bank_mask:0xf bound_ctrl:1
	v_add_f32_dpp v2, v2, v2 row_shr:2 row_mask:0xf bank_mask:0xf bound_ctrl:1
	v_add_f32_dpp v3, v3, v3 row_shr:2 row_mask:0xf bank_mask:0xf bound_ctrl:1
	v_add_f32_dpp v0, v0, v0 row_shr:4 row_mask:0xf bank_mask:0xf bound_ctrl:1
	v_add_f32_dpp v1, v1, v1 row_shr:4 row_mask:0xf bank_mask:0xf bound_ctrl:1
	v_add_f32_dpp v2, v2, v2 row_shr:4 row_mask:0xf bank_mask:0xf bound_ctrl:1
	v_add_f32_dpp v3, v3, v3 row_shr:4 row_mask:0xf bank_mask:0xf bound_ctrl:1
	v_add_f32_dpp v0, v0, v0 row_shr:8 row_mask:0xf bank_mask:0xf bound_ctrl:1
	v_add_f32_dpp v1, v1, v1 row_shr:8 row_mask:0xf bank_mask:0xf bound_ctrl:1
	v_add_f32_dpp v2, v2, v2 row_shr:8 row_mask:0xf bank_mask:0xf bound_ctrl:1
	v_add_f32_dpp v3, v3, v3 row_shr:8 row_mask:0xf bank_mask:0xf bound_ctrl:1
	v_add_f32_dpp v0, v0, v0 row_bcast:15 row_mask:0xa bank_mask:0xf
	v_add_f32_dpp v1, v1, v1 row_bcast:15 row_mask:0xa bank_mask:0xf
	v_add_f32_dpp v2, v2, v2 row_bcast:15 row_mask:0xa bank_mask:0xf
	v_add_f32_dpp v3, v3, v3 row_bcast:15 row_mask:0xa bank_mask:0xf
	v_add_f32_dpp v0, v0, v0 row_bcast:31 row_mask:0xc bank_mask:0xf
	v_add_f32_dpp v1, v1, v1 row_bcast:31 row_mask:0xc bank_mask:0xf
	v_add_f32_dpp v2, v2, v2 row_bcast:31 row_mask:0xc bank_mask:0xf
	v_add_f32_dpp v3, v3, v3 row_bcast:31 row_mask:0xc bank_mask:0xf
	v_lshlrev_b32_e32 v10, 16, v47
	v_and_b32_e32 v11, 0xffff0000, v47
	s_add_i32 s24, s48, s54
	ds_write2_b32 v59, v2, v3 offset1:1
	ds_write2_b32 v59, v0, v1 offset0:2 offset1:3
	ds_read2_b32 v[0:1], v59 offset0:6 offset1:7
	ds_read2_b32 v[2:3], v59 offset0:4 offset1:5
	s_waitcnt lgkmcnt(0)
	v_add_f32_dpp v0, v0, v0 row_shr:1 row_mask:0xf bank_mask:0xf bound_ctrl:1
	v_add_f32_dpp v1, v1, v1 row_shr:1 row_mask:0xf bank_mask:0xf bound_ctrl:1
	v_add_f32_dpp v2, v2, v2 row_shr:1 row_mask:0xf bank_mask:0xf bound_ctrl:1
	v_add_f32_dpp v3, v3, v3 row_shr:1 row_mask:0xf bank_mask:0xf bound_ctrl:1
	v_add_f32_dpp v0, v0, v0 row_shr:2 row_mask:0xf bank_mask:0xf bound_ctrl:1
	v_add_f32_dpp v1, v1, v1 row_shr:2 row_mask:0xf bank_mask:0xf bound_ctrl:1
	v_add_f32_dpp v2, v2, v2 row_shr:2 row_mask:0xf bank_mask:0xf bound_ctrl:1
	v_add_f32_dpp v3, v3, v3 row_shr:2 row_mask:0xf bank_mask:0xf bound_ctrl:1
	v_add_f32_dpp v0, v0, v0 row_shr:4 row_mask:0xf bank_mask:0xf bound_ctrl:1
	v_add_f32_dpp v1, v1, v1 row_shr:4 row_mask:0xf bank_mask:0xf bound_ctrl:1
	v_add_f32_dpp v2, v2, v2 row_shr:4 row_mask:0xf bank_mask:0xf bound_ctrl:1
	v_add_f32_dpp v3, v3, v3 row_shr:4 row_mask:0xf bank_mask:0xf bound_ctrl:1
	v_add_f32_dpp v0, v0, v0 row_shr:8 row_mask:0xf bank_mask:0xf bound_ctrl:1
	v_add_f32_dpp v1, v1, v1 row_shr:8 row_mask:0xf bank_mask:0xf bound_ctrl:1
	v_add_f32_dpp v2, v2, v2 row_shr:8 row_mask:0xf bank_mask:0xf bound_ctrl:1
	v_add_f32_dpp v3, v3, v3 row_shr:8 row_mask:0xf bank_mask:0xf bound_ctrl:1
	v_add_f32_dpp v0, v0, v0 row_bcast:15 row_mask:0xa bank_mask:0xf
	v_add_f32_dpp v1, v1, v1 row_bcast:15 row_mask:0xa bank_mask:0xf
	v_add_f32_dpp v2, v2, v2 row_bcast:15 row_mask:0xa bank_mask:0xf
	v_add_f32_dpp v3, v3, v3 row_bcast:15 row_mask:0xa bank_mask:0xf
	v_add_f32_dpp v0, v0, v0 row_bcast:31 row_mask:0xc bank_mask:0xf
	v_add_f32_dpp v1, v1, v1 row_bcast:31 row_mask:0xc bank_mask:0xf
	v_add_f32_dpp v2, v2, v2 row_bcast:31 row_mask:0xc bank_mask:0xf
	v_add_f32_dpp v3, v3, v3 row_bcast:31 row_mask:0xc bank_mask:0xf
	ds_write2_b32 v59, v2, v3 offset0:4 offset1:5
	ds_write2_b32 v59, v0, v1 offset0:6 offset1:7
	s_waitcnt lgkmcnt(0)
	s_barrier
; DI float bflo(unsigned u) { return __uint_as_float(u << 16); }
; DI float bfhi(unsigned u) { return __uint_as_float(u & 0xffff0000u); }
; DI bf16_t f2bf(float f) { return (bf16_t)(cvtpk(f, f) & 0xffffu); }
; DI void phase_gla1(ArgsP a, int tb_, int l, char* shm, int vcu, int G) {
;     ...
;             { const float kv[8] = {bflo(kw.x), bfhi(kw.x), bflo(kw.y), bfhi(kw.y), bflo(kw.z), bfhi(kw.z), bflo(kw.w), bfhi(kw.w)};
; #pragma unroll
;               for (int kk = 0; kk < 8; ++kk) { const int kd = kg * 8 + kk; *(bf16_t*)(KT + kd * 144 + j * 2) = f2bf(kv[kk] * __expf(LA[jl * 65 + kd] - LA[j * 65 + kd])); }
;               const unsigned vv[8] = {v0.x, v0.y, v0.z, v0.w, v1.x, v1.y, v1.z, v1.w};
; #pragma unroll
;               for (int q = 0; q < 8; ++q) { *(bf16_t*)(VT + (kg * 16 + 2 * q) * 144 + j * 2) = (bf16_t)(vv[q] & 0xffffu); *(bf16_t*)(VT + (kg * 16 + 2 * q + 1) * 144 + j * 2) = (bf16_t)(vv[q] >> 16); } }
;             if (tid < 64) DEC[(size_t)item * 64 + tid] = __expf(LA[jl * 65 + tid]);
	ds_read2_b32 v[0:1], v12 offset1:1
	ds_read2_b32 v[2:3], v54 offset1:1
	v_lshlrev_b32_e32 v4, 16, v44
	v_and_b32_e32 v5, 0xffff0000, v44
	v_lshlrev_b32_e32 v6, 16, v45
	v_and_b32_e32 v7, 0xffff0000, v45
	s_waitcnt lgkmcnt(0)
	v_sub_f32_e32 v0, v0, v2
	v_mul_f32_e32 v0, 0x3fb8aa3b, v0
	v_exp_f32_e32 v0, v0
	s_nop 0
	v_mul_f32_e32 v0, v0, v4
	v_cvt_pk_bf16_f32 v0, v0, s0
	ds_write_b16 v75, v0 offset:16640
	v_sub_f32_e32 v0, v1, v3
	v_mul_f32_e32 v0, 0x3fb8aa3b, v0
	v_exp_f32_e32 v0, v0
	s_nop 0
	v_mul_f32_e32 v0, v0, v5
	v_cvt_pk_bf16_f32 v0, v0, s0
	ds_write_b16 v76, v0 offset:16640
	ds_read2_b32 v[0:1], v12 offset0:2 offset1:3
	ds_read2_b32 v[2:3], v54 offset0:2 offset1:3
	s_waitcnt lgkmcnt(0)
	v_sub_f32_e32 v0, v0, v2
	v_mul_f32_e32 v0, 0x3fb8aa3b, v0
	v_exp_f32_e32 v0, v0
	s_nop 0
	v_mul_f32_e32 v0, v0, v6
	v_cvt_pk_bf16_f32 v0, v0, s0
	ds_write_b16 v76, v0 offset:16784
	v_sub_f32_e32 v0, v1, v3
	v_mul_f32_e32 v0, 0x3fb8aa3b, v0
	v_exp_f32_e32 v0, v0
	s_nop 0
	v_mul_f32_e32 v0, v0, v7
	v_cvt_pk_bf16_f32 v0, v0, s0
	ds_write_b16 v76, v0 offset:16928
	ds_read2_b32 v[0:1], v12 offset0:4 offset1:5
	ds_read2_b32 v[2:3], v54 offset0:4 offset1:5
	s_waitcnt lgkmcnt(0)
	v_sub_f32_e32 v0, v0, v2
	v_mul_f32_e32 v0, 0x3fb8aa3b, v0
	v_exp_f32_e32 v0, v0
	s_nop 0
	v_mul_f32_e32 v0, v0, v8
	v_cvt_pk_bf16_f32 v0, v0, s0
	ds_write_b16 v76, v0 offset:17072
	v_sub_f32_e32 v0, v1, v3
	v_mul_f32_e32 v0, 0x3fb8aa3b, v0
	v_exp_f32_e32 v0, v0
	s_nop 0
	v_mul_f32_e32 v0, v0, v9
	v_cvt_pk_bf16_f32 v0, v0, s0
	ds_write_b16 v76, v0 offset:17216
	ds_read2_b32 v[0:1], v12 offset0:6 offset1:7
	ds_read2_b32 v[2:3], v54 offset0:6 offset1:7
	s_waitcnt lgkmcnt(0)
	v_sub_f32_e32 v0, v0, v2
	v_mul_f32_e32 v0, 0x3fb8aa3b, v0
	v_exp_f32_e32 v0, v0
	s_nop 0
	v_mul_f32_e32 v0, v0, v10
	v_cvt_pk_bf16_f32 v0, v0, s0
	ds_write_b16 v76, v0 offset:17360
	v_sub_f32_e32 v0, v1, v3
	v_mul_f32_e32 v0, 0x3fb8aa3b, v0
	v_exp_f32_e32 v0, v0
	s_nop 0
	v_mul_f32_e32 v0, v0, v11
	v_cvt_pk_bf16_f32 v0, v0, s0
	ds_write_b16 v76, v0 offset:17504
	ds_write_b16 v77, v24 offset:25856
	ds_write_b16_d16_hi v77, v24 offset:26000
	ds_write_b16 v77, v25 offset:26144
	ds_write_b16_d16_hi v77, v25 offset:26288
	ds_write_b16 v77, v26 offset:26432
	ds_write_b16_d16_hi v77, v26 offset:26576
	ds_write_b16 v77, v27 offset:26720
	ds_write_b16_d16_hi v77, v27 offset:26864
	ds_write_b16 v77, v20 offset:27008
	ds_write_b16_d16_hi v77, v20 offset:27152
	ds_write_b16 v77, v21 offset:27296
	ds_write_b16_d16_hi v77, v21 offset:27440
	ds_write_b16 v77, v22 offset:27584
	ds_write_b16_d16_hi v77, v22 offset:27728
	ds_write_b16 v77, v23 offset:27872
	ds_write_b16_d16_hi v77, v23 offset:28016
	s_and_saveexec_b64 s[44:45], s[20:21]
	s_xor_b64 s[44:45], exec, s[44:45]
	s_ashr_i32 s25, s24, 31
	s_or_saveexec_b64 s[44:45], s[44:45]
	v_mov_b64_e32 v[20:21], s[24:25]
	s_xor_b64 exec, exec, s[44:45]
	s_cbranch_execz .LBB0_1259
	ds_read_b32 v0, v80
	s_ashr_i32 s25, s24, 31
	s_lshl_b64 s[60:61], s[24:25], 8
	v_mov_b64_e32 v[20:21], s[24:25]
	s_waitcnt lgkmcnt(0)
	v_mul_f32_e32 v0, 0x3fb8aa3b, v0
	v_exp_f32_e32 v2, v0
	v_lshl_add_u64 v[0:1], v[50:51], 0, s[60:61]
	global_store_dword v[0:1], v2, off
	s_branch .LBB0_1259

; DI int crow(int r, int hi) { return (r & 3) + 8 * (r >> 2) + 4 * hi; }
; DI float logsig(float x) { return fminf(x, 0.f) - __logf(1.f + __expf(-fabsf(x))); }
; DI void phase_gla3(ArgsP a, int tb_, int l, bool with_ctx, char* shm, int vcu, int G) {
;     ...
;             { f32x16 acc;
; #pragma unroll
;               for (int r = 0; r < 16; ++r) acc[r] = 0.f;
;               acc = __builtin_amdgcn_mfma_f32_32x32x16_bf16(gfr, wfr, acc, 0, 0, 0);
; #pragma unroll
;               for (int r = 0; r < 16; ++r) LA[ldir * 4160 + (ljb * 32 + crow(r, hi)) * 65 + lkb * 32 + r32] = logsig(acc[r] + bias) * (1.f / 16.f); }
.LBB0_1417:
	v_mfma_f32_32x32x16_bf16 v[0:15], v[0:3], v[16:19], 0
	v_lshlrev_b32_e32 v118, 16, v54
	v_and_b32_e32 v119, 0xffff0000, v54
	v_mul_f32_e64 v118, v118, s90
	v_mul_f32_e64 v119, v119, s90
	v_lshlrev_b32_e32 v120, 16, v50
	v_and_b32_e32 v121, 0xffff0000, v50
	v_lshlrev_b32_e32 v54, 16, v55
	v_and_b32_e32 v55, 0xffff0000, v55
	s_nop 3
	v_add_f32_e32 v0, v111, v0
	v_mul_f32_e64 v79, |v0|, s77
	v_exp_f32_e32 v79, v79
	v_add_f32_e32 v1, v111, v1
	v_mul_f32_e64 v81, |v1|, s77
	v_exp_f32_e32 v81, v81
	v_add_f32_e32 v79, 1.0, v79
	v_cmp_gt_f32_e32 vcc, s76, v79
	v_min_f32_e32 v0, 0, v0
	v_add_f32_e32 v81, 1.0, v81
	v_cndmask_b32_e64 v114, 0, 32, vcc
	v_ldexp_f32 v79, v79, v114
	v_log_f32_e32 v79, v79
	v_cmp_gt_f32_e64 s[54:55], s76, v81
	v_cndmask_b32_e32 v114, 0, v240, vcc
	v_add_f32_e32 v2, v111, v2
	v_cndmask_b32_e64 v115, 0, 32, s[54:55]
	v_ldexp_f32 v81, v81, v115
	v_mul_f32_e32 v115, 0x3f317217, v79
	v_log_f32_e32 v81, v81
	v_fma_f32 v115, v79, s62, -v115
	v_fmac_f32_e32 v115, 0x3377d1cf, v79
	v_cmp_lt_f32_e64 vcc, |v79|, s95
	v_fmac_f32_e32 v115, 0x3f317217, v79
	v_mul_f32_e32 v116, 0x3f317217, v81
	v_cndmask_b32_e32 v79, v79, v115, vcc
	v_sub_f32_e32 v79, v79, v114
	v_sub_f32_e32 v0, v0, v79
	v_fma_f32 v79, v81, s62, -v116
	v_fmac_f32_e32 v79, 0x3377d1cf, v81
	v_fmac_f32_e32 v79, 0x3f317217, v81
	v_cmp_lt_f32_e64 vcc, |v81|, s95
	v_cndmask_b32_e64 v114, 0, v240, s[54:55]
	v_min_f32_e32 v1, 0, v1
	v_cndmask_b32_e32 v79, v81, v79, vcc
	v_mul_f32_e64 v81, |v2|, s77
	v_exp_f32_e32 v81, v81
	v_sub_f32_e32 v79, v79, v114
	v_sub_f32_e32 v1, v1, v79
	v_mul_f32_e32 v0, 0x3d800000, v0
	v_add_f32_e32 v79, 1.0, v81
	v_cmp_gt_f32_e32 vcc, s76, v79
	v_mul_f32_e32 v1, 0x3d800000, v1
	ds_write2_b32 v99, v0, v1 offset1:65
	v_cndmask_b32_e64 v81, 0, 32, vcc
	v_ldexp_f32 v79, v79, v81
	v_log_f32_e32 v79, v79
	v_min_f32_e32 v0, 0, v2
	v_add_f32_e32 v2, v111, v3
	v_mul_f32_e64 v3, |v2|, s77
	v_exp_f32_e32 v3, v3
	v_mul_f32_e32 v1, 0x3f317217, v79
	v_fma_f32 v1, v79, s62, -v1
	v_fmac_f32_e32 v1, 0x3377d1cf, v79
	v_fmac_f32_e32 v1, 0x3f317217, v79
	v_cmp_lt_f32_e64 s[54:55], |v79|, s95
	v_add_f32_e32 v3, 1.0, v3
	v_pk_mul_f32 v[54:55], v[54:55], s[90:91] op_sel_hi:[1,0]
	v_cndmask_b32_e64 v1, v79, v1, s[54:55]
	v_cndmask_b32_e32 v79, 0, v240, vcc
	v_cmp_gt_f32_e32 vcc, s76, v3
	v_sub_f32_e32 v1, v1, v79
	v_sub_f32_e32 v0, v0, v1
	v_cndmask_b32_e64 v79, 0, 32, vcc
	v_ldexp_f32 v3, v3, v79
	v_log_f32_e32 v3, v3
	v_min_f32_e32 v1, 0, v2
	v_cndmask_b32_e32 v79, 0, v240, vcc
	v_mul_f32_e32 v0, 0x3d800000, v0
	v_mul_f32_e32 v2, 0x3f317217, v3
	v_fma_f32 v2, v3, s62, -v2
	v_fmac_f32_e32 v2, 0x3377d1cf, v3
	v_fmac_f32_e32 v2, 0x3f317217, v3
	v_cmp_lt_f32_e64 s[54:55], |v3|, s95
	v_lshlrev_b32_e32 v50, 16, v51
	v_and_b32_e32 v51, 0xffff0000, v51
	v_cndmask_b32_e64 v2, v3, v2, s[54:55]
	v_add_f32_e32 v3, v111, v4
	v_mul_f32_e64 v4, |v3|, s77
	v_exp_f32_e32 v4, v4
	v_sub_f32_e32 v2, v2, v79
	v_sub_f32_e32 v1, v1, v2
	v_mul_f32_e32 v1, 0x3d800000, v1
	v_add_f32_e32 v2, 1.0, v4
	v_cmp_gt_f32_e32 vcc, s76, v2
	ds_write2_b32 v99, v0, v1 offset0:130 offset1:195
	v_min_f32_e32 v0, 0, v3
	v_cndmask_b32_e64 v4, 0, 32, vcc
	v_ldexp_f32 v2, v2, v4
	v_log_f32_e32 v2, v2
	v_add_f32_e32 v3, v111, v5
	v_mul_f32_e64 v4, |v3|, s77
	v_exp_f32_e32 v4, v4
	v_mul_f32_e32 v1, 0x3f317217, v2
	v_fma_f32 v1, v2, s62, -v1
	v_fmac_f32_e32 v1, 0x3377d1cf, v2
	v_fmac_f32_e32 v1, 0x3f317217, v2
	v_cmp_lt_f32_e64 s[54:55], |v2|, s95
	s_cmp_lt_u32 s70, 4
	v_add_u32_e32 v113, 0x200, v113
	v_cndmask_b32_e64 v1, v2, v1, s[54:55]
	v_cndmask_b32_e32 v2, 0, v240, vcc
	v_sub_f32_e32 v1, v1, v2
	v_add_f32_e32 v2, 1.0, v4
	v_cmp_gt_f32_e32 vcc, s76, v2
	v_sub_f32_e32 v0, v0, v1
	v_min_f32_e32 v1, 0, v3
	v_cndmask_b32_e64 v4, 0, 32, vcc
	v_ldexp_f32 v2, v2, v4
	v_log_f32_e32 v2, v2
	v_add_f32_e32 v4, v111, v6
	v_mul_f32_e64 v5, |v4|, s77
	v_exp_f32_e32 v5, v5
	v_mul_f32_e32 v3, 0x3f317217, v2
	v_fma_f32 v3, v2, s62, -v3
	v_fmac_f32_e32 v3, 0x3377d1cf, v2
	v_fmac_f32_e32 v3, 0x3f317217, v2
	v_cmp_lt_f32_e64 s[54:55], |v2|, s95
	v_mul_f32_e32 v0, 0x3d800000, v0
	s_nop 0
	v_cndmask_b32_e64 v2, v2, v3, s[54:55]
	v_cndmask_b32_e32 v3, 0, v240, vcc
	v_sub_f32_e32 v2, v2, v3
	v_sub_f32_e32 v1, v1, v2
	v_add_f32_e32 v2, 1.0, v5
	v_cmp_gt_f32_e32 vcc, s76, v2
	v_mul_f32_e32 v1, 0x3d800000, v1
	s_nop 0
	v_cndmask_b32_e64 v3, 0, 32, vcc
	v_ldexp_f32 v2, v2, v3
	v_log_f32_e32 v2, v2
	v_add_u32_e32 v3, 0x800, v99
	ds_write2_b32 v3, v0, v1 offset0:8 offset1:73
	v_min_f32_e32 v0, 0, v4
	v_add_f32_e32 v4, v111, v7
	v_mul_f32_e32 v1, 0x3f317217, v2
	v_mul_f32_e64 v5, |v4|, s77
	v_fma_f32 v1, v2, s62, -v1
	v_exp_f32_e32 v5, v5
	v_fmac_f32_e32 v1, 0x3377d1cf, v2
	v_fmac_f32_e32 v1, 0x3f317217, v2
	v_cmp_lt_f32_e64 s[54:55], |v2|, s95
	s_nop 1
	v_cndmask_b32_e64 v1, v2, v1, s[54:55]
	v_cndmask_b32_e32 v2, 0, v240, vcc
	v_sub_f32_e32 v1, v1, v2
	v_add_f32_e32 v2, 1.0, v5
	v_cmp_gt_f32_e32 vcc, s76, v2
	v_sub_f32_e32 v0, v0, v1
	v_min_f32_e32 v1, 0, v4
	v_cndmask_b32_e64 v5, 0, 32, vcc
	v_ldexp_f32 v2, v2, v5
	v_log_f32_e32 v2, v2
	v_cndmask_b32_e32 v6, 0, v240, vcc
	v_mul_f32_e32 v0, 0x3d800000, v0
	v_mul_f32_e32 v4, 0x3f317217, v2
	v_fma_f32 v4, v2, s62, -v4
	v_fmac_f32_e32 v4, 0x3377d1cf, v2
	v_fmac_f32_e32 v4, 0x3f317217, v2
	v_cmp_lt_f32_e64 s[54:55], |v2|, s95
	s_nop 1
	v_cndmask_b32_e64 v2, v2, v4, s[54:55]
	v_add_f32_e32 v4, v111, v8
	v_mul_f32_e64 v5, |v4|, s77
	v_exp_f32_e32 v5, v5
	v_sub_f32_e32 v2, v2, v6
	v_sub_f32_e32 v1, v1, v2
	v_mul_f32_e32 v1, 0x3d800000, v1
	v_add_f32_e32 v2, 1.0, v5
	v_cmp_gt_f32_e32 vcc, s76, v2
	ds_write2_b32 v3, v0, v1 offset0:138 offset1:203
	v_add_f32_e32 v3, v111, v9
; DI int crow(int r, int hi) { return (r & 3) + 8 * (r >> 2) + 4 * hi; }
; DI float logsig(float x) { return fminf(x, 0.f) - __logf(1.f + __expf(-fabsf(x))); }
; DI void phase_gla3(ArgsP a, int tb_, int l, bool with_ctx, char* shm, int vcu, int G) {
;     ...
;               acc = __builtin_amdgcn_mfma_f32_32x32x16_bf16(gfr, wfr, acc, 0, 0, 0);
; #pragma unroll
;               for (int r = 0; r < 16; ++r) LA[ldir * 4160 + (ljb * 32 + crow(r, hi)) * 65 + lkb * 32 + r32] = logsig(acc[r] + bias) * (1.f / 16.f); }
;             __syncthreads();
	v_cndmask_b32_e64 v5, 0, 32, vcc
	v_ldexp_f32 v2, v2, v5
	v_log_f32_e32 v2, v2
	v_min_f32_e32 v0, 0, v4
	v_mul_f32_e64 v4, |v3|, s77
	v_exp_f32_e32 v4, v4
	v_mul_f32_e32 v1, 0x3f317217, v2
	v_fma_f32 v1, v2, s62, -v1
	v_fmac_f32_e32 v1, 0x3377d1cf, v2
	v_fmac_f32_e32 v1, 0x3f317217, v2
	v_cmp_lt_f32_e64 s[54:55], |v2|, s95
	s_nop 1
	v_cndmask_b32_e64 v1, v2, v1, s[54:55]
	v_cndmask_b32_e32 v2, 0, v240, vcc
	v_sub_f32_e32 v1, v1, v2
	v_add_f32_e32 v2, 1.0, v4
	v_cmp_gt_f32_e32 vcc, s76, v2
	v_sub_f32_e32 v0, v0, v1
	v_min_f32_e32 v1, 0, v3
	v_cndmask_b32_e64 v4, 0, 32, vcc
	v_ldexp_f32 v2, v2, v4
	v_log_f32_e32 v2, v2
	v_add_f32_e32 v4, v111, v10
	v_mul_f32_e64 v5, |v4|, s77
	v_exp_f32_e32 v5, v5
	v_mul_f32_e32 v3, 0x3f317217, v2
	v_fma_f32 v3, v2, s62, -v3
	v_fmac_f32_e32 v3, 0x3377d1cf, v2
	v_fmac_f32_e32 v3, 0x3f317217, v2
	v_cmp_lt_f32_e64 s[54:55], |v2|, s95
	v_mul_f32_e32 v0, 0x3d800000, v0
	s_nop 0
	v_cndmask_b32_e64 v2, v2, v3, s[54:55]
	v_cndmask_b32_e32 v3, 0, v240, vcc
	v_sub_f32_e32 v2, v2, v3
	v_sub_f32_e32 v1, v1, v2
	v_add_f32_e32 v2, 1.0, v5
	v_cmp_gt_f32_e32 vcc, s76, v2
	v_mul_f32_e32 v1, 0x3d800000, v1
	s_nop 0
	v_cndmask_b32_e64 v3, 0, 32, vcc
	v_ldexp_f32 v2, v2, v3
	v_log_f32_e32 v2, v2
	v_add_u32_e32 v3, 0x1000, v99
	ds_write2_b32 v3, v0, v1 offset0:16 offset1:81
	v_min_f32_e32 v0, 0, v4
	v_add_f32_e32 v4, v111, v11
	v_mul_f32_e32 v1, 0x3f317217, v2
	v_mul_f32_e64 v5, |v4|, s77
	v_fma_f32 v1, v2, s62, -v1
	v_exp_f32_e32 v5, v5
	v_fmac_f32_e32 v1, 0x3377d1cf, v2
	v_fmac_f32_e32 v1, 0x3f317217, v2
	v_cmp_lt_f32_e64 s[54:55], |v2|, s95
	s_nop 1
	v_cndmask_b32_e64 v1, v2, v1, s[54:55]
	v_cndmask_b32_e32 v2, 0, v240, vcc
	v_sub_f32_e32 v1, v1, v2
	v_add_f32_e32 v2, 1.0, v5
	v_cmp_gt_f32_e32 vcc, s76, v2
	v_sub_f32_e32 v0, v0, v1
	v_min_f32_e32 v1, 0, v4
	v_cndmask_b32_e64 v5, 0, 32, vcc
	v_ldexp_f32 v2, v2, v5
	v_log_f32_e32 v2, v2
	v_cndmask_b32_e32 v6, 0, v240, vcc
	v_mul_f32_e32 v0, 0x3d800000, v0
	v_mul_f32_e32 v4, 0x3f317217, v2
	v_fma_f32 v4, v2, s62, -v4
	v_fmac_f32_e32 v4, 0x3377d1cf, v2
	v_fmac_f32_e32 v4, 0x3f317217, v2
	v_cmp_lt_f32_e64 s[54:55], |v2|, s95
	s_nop 1
	v_cndmask_b32_e64 v2, v2, v4, s[54:55]
	v_add_f32_e32 v4, v111, v12
	v_mul_f32_e64 v5, |v4|, s77
	v_exp_f32_e32 v5, v5
	v_sub_f32_e32 v2, v2, v6
	v_sub_f32_e32 v1, v1, v2
	v_mul_f32_e32 v1, 0x3d800000, v1
	v_add_f32_e32 v2, 1.0, v5
	v_cmp_gt_f32_e32 vcc, s76, v2
	ds_write2_b32 v3, v0, v1 offset0:146 offset1:211
	v_add_f32_e32 v3, v111, v13
	v_cndmask_b32_e64 v5, 0, 32, vcc
	v_ldexp_f32 v2, v2, v5
	v_log_f32_e32 v2, v2
	v_min_f32_e32 v0, 0, v4
	v_mul_f32_e64 v4, |v3|, s77
	v_exp_f32_e32 v4, v4
	v_mul_f32_e32 v1, 0x3f317217, v2
	v_fma_f32 v1, v2, s62, -v1
	v_fmac_f32_e32 v1, 0x3377d1cf, v2
	v_fmac_f32_e32 v1, 0x3f317217, v2
	v_cmp_lt_f32_e64 s[54:55], |v2|, s95
	s_nop 1
	v_cndmask_b32_e64 v1, v2, v1, s[54:55]
	v_cndmask_b32_e32 v2, 0, v240, vcc
	v_sub_f32_e32 v1, v1, v2
	v_add_f32_e32 v2, 1.0, v4
	v_cmp_gt_f32_e32 vcc, s76, v2
	v_sub_f32_e32 v0, v0, v1
	v_min_f32_e32 v1, 0, v3
	v_cndmask_b32_e64 v4, 0, 32, vcc
	v_ldexp_f32 v2, v2, v4
	v_log_f32_e32 v2, v2
	v_add_f32_e32 v4, v111, v14
	v_mul_f32_e64 v5, |v4|, s77
	v_exp_f32_e32 v5, v5
	v_mul_f32_e32 v3, 0x3f317217, v2
	v_fma_f32 v3, v2, s62, -v3
	v_fmac_f32_e32 v3, 0x3377d1cf, v2
	v_fmac_f32_e32 v3, 0x3f317217, v2
	v_cmp_lt_f32_e64 s[54:55], |v2|, s95
	v_mul_f32_e32 v0, 0x3d800000, v0
	s_nop 0
	v_cndmask_b32_e64 v2, v2, v3, s[54:55]
	v_cndmask_b32_e32 v3, 0, v240, vcc
	v_sub_f32_e32 v2, v2, v3
	v_sub_f32_e32 v1, v1, v2
	v_add_f32_e32 v2, 1.0, v5
	v_cmp_gt_f32_e32 vcc, s76, v2
	v_mul_f32_e32 v1, 0x3d800000, v1
	s_nop 0
	v_cndmask_b32_e64 v3, 0, 32, vcc
	v_ldexp_f32 v2, v2, v3
	v_log_f32_e32 v2, v2
	v_add_u32_e32 v3, 0x1800, v99
	ds_write2_b32 v3, v0, v1 offset0:24 offset1:89
	v_min_f32_e32 v0, 0, v4
	v_add_f32_e32 v4, v111, v15
	v_mul_f32_e32 v1, 0x3f317217, v2
	v_mul_f32_e64 v5, |v4|, s77
	v_fma_f32 v1, v2, s62, -v1
	v_exp_f32_e32 v5, v5
	v_fmac_f32_e32 v1, 0x3377d1cf, v2
	v_fmac_f32_e32 v1, 0x3f317217, v2
	v_cmp_lt_f32_e64 s[54:55], |v2|, s95
	s_nop 1
	v_cndmask_b32_e64 v1, v2, v1, s[54:55]
	v_cndmask_b32_e32 v2, 0, v240, vcc
	v_sub_f32_e32 v1, v1, v2
	v_add_f32_e32 v2, 1.0, v5
	v_cmp_gt_f32_e32 vcc, s76, v2
	v_sub_f32_e32 v0, v0, v1
	v_min_f32_e32 v1, 0, v4
	v_cndmask_b32_e64 v5, 0, 32, vcc
	v_ldexp_f32 v2, v2, v5
	v_log_f32_e32 v2, v2
	v_mul_f32_e32 v0, 0x3d800000, v0
	v_mul_f32_e32 v4, 0x3f317217, v2
	v_fma_f32 v4, v2, s62, -v4
	v_fmac_f32_e32 v4, 0x3377d1cf, v2
	v_fmac_f32_e32 v4, 0x3f317217, v2
	v_cmp_lt_f32_e64 s[54:55], |v2|, s95
	s_nop 1
	v_cndmask_b32_e64 v2, v2, v4, s[54:55]
	v_cndmask_b32_e32 v4, 0, v240, vcc
	v_sub_f32_e32 v2, v2, v4
	v_sub_f32_e32 v1, v1, v2
	v_mul_f32_e32 v1, 0x3d800000, v1
	ds_write2_b32 v3, v0, v1 offset0:154 offset1:219
	s_waitcnt lgkmcnt(0)
	s_barrier
; DI void phase_gla3(ArgsP a, int tb_, int l, bool with_ctx, char* shm, int vcu, int G) {
;     ...
;             { const int dir = wid >> 2;
; #pragma unroll
;               for (int i = 0; i < 16; ++i) { const int kd = (wid & 3) * 16 + i, jj = dir ? 63 - lane : lane; const float x = scan64(LA[dir * 4160 + jj * 65 + kd], lane); LA[dir * 4160 + jj * 65 + kd] = x; } }
;             __syncthreads();
	s_cselect_b32 s54, 3, 0x47
	s_cselect_b32 s55, s74, s94
	s_add_i32 s70, s70, 8
	ds_read2_b32 v[0:1], v67 offset1:1
	ds_read2_b32 v[2:3], v67 offset0:2 offset1:3
	ds_read2_b32 v[4:5], v67 offset0:4 offset1:5
	ds_read2_b32 v[6:7], v67 offset0:6 offset1:7
	ds_read2_b32 v[8:9], v67 offset0:8 offset1:9
	ds_read2_b32 v[10:11], v67 offset0:10 offset1:11
	ds_read2_b32 v[14:15], v67 offset0:12 offset1:13
	ds_read2_b32 v[114:115], v67 offset0:14 offset1:15
	s_waitcnt lgkmcnt(0)
	v_add_f32_dpp v0, v0, v0 row_shr:1 row_mask:0xf bank_mask:0xf bound_ctrl:1
	v_add_f32_dpp v1, v1, v1 row_shr:1 row_mask:0xf bank_mask:0xf bound_ctrl:1
	v_add_f32_dpp v2, v2, v2 row_shr:1 row_mask:0xf bank_mask:0xf bound_ctrl:1
	v_add_f32_dpp v3, v3, v3 row_shr:1 row_mask:0xf bank_mask:0xf bound_ctrl:1
	v_add_f32_dpp v4, v4, v4 row_shr:1 row_mask:0xf bank_mask:0xf bound_ctrl:1
	v_add_f32_dpp v5, v5, v5 row_shr:1 row_mask:0xf bank_mask:0xf bound_ctrl:1
	v_add_f32_dpp v6, v6, v6 row_shr:1 row_mask:0xf bank_mask:0xf bound_ctrl:1
	v_add_f32_dpp v7, v7, v7 row_shr:1 row_mask:0xf bank_mask:0xf bound_ctrl:1
	v_add_f32_dpp v8, v8, v8 row_shr:1 row_mask:0xf bank_mask:0xf bound_ctrl:1
	v_add_f32_dpp v9, v9, v9 row_shr:1 row_mask:0xf bank_mask:0xf bound_ctrl:1
	v_add_f32_dpp v10, v10, v10 row_shr:1 row_mask:0xf bank_mask:0xf bound_ctrl:1
	v_add_f32_dpp v11, v11, v11 row_shr:1 row_mask:0xf bank_mask:0xf bound_ctrl:1
	v_add_f32_dpp v14, v14, v14 row_shr:1 row_mask:0xf bank_mask:0xf bound_ctrl:1
	v_add_f32_dpp v15, v15, v15 row_shr:1 row_mask:0xf bank_mask:0xf bound_ctrl:1
	v_add_f32_dpp v114, v114, v114 row_shr:1 row_mask:0xf bank_mask:0xf bound_ctrl:1
	v_add_f32_dpp v115, v115, v115 row_shr:1 row_mask:0xf bank_mask:0xf bound_ctrl:1
	v_add_f32_dpp v0, v0, v0 row_shr:2 row_mask:0xf bank_mask:0xf bound_ctrl:1
	v_add_f32_dpp v1, v1, v1 row_shr:2 row_mask:0xf bank_mask:0xf bound_ctrl:1
	v_add_f32_dpp v2, v2, v2 row_shr:2 row_mask:0xf bank_mask:0xf bound_ctrl:1
	v_add_f32_dpp v3, v3, v3 row_shr:2 row_mask:0xf bank_mask:0xf bound_ctrl:1
	v_add_f32_dpp v4, v4, v4 row_shr:2 row_mask:0xf bank_mask:0xf bound_ctrl:1
	v_add_f32_dpp v5, v5, v5 row_shr:2 row_mask:0xf bank_mask:0xf bound_ctrl:1
	v_add_f32_dpp v6, v6, v6 row_shr:2 row_mask:0xf bank_mask:0xf bound_ctrl:1
	v_add_f32_dpp v7, v7, v7 row_shr:2 row_mask:0xf bank_mask:0xf bound_ctrl:1
	v_add_f32_dpp v8, v8, v8 row_shr:2 row_mask:0xf bank_mask:0xf bound_ctrl:1
	v_add_f32_dpp v9, v9, v9 row_shr:2 row_mask:0xf bank_mask:0xf bound_ctrl:1
	v_add_f32_dpp v10, v10, v10 row_shr:2 row_mask:0xf bank_mask:0xf bound_ctrl:1
	v_add_f32_dpp v11, v11, v11 row_shr:2 row_mask:0xf bank_mask:0xf bound_ctrl:1
	v_add_f32_dpp v14, v14, v14 row_shr:2 row_mask:0xf bank_mask:0xf bound_ctrl:1
	v_add_f32_dpp v15, v15, v15 row_shr:2 row_mask:0xf bank_mask:0xf bound_ctrl:1
	v_add_f32_dpp v114, v114, v114 row_shr:2 row_mask:0xf bank_mask:0xf bound_ctrl:1
	v_add_f32_dpp v115, v115, v115 row_shr:2 row_mask:0xf bank_mask:0xf bound_ctrl:1
	v_add_f32_dpp v0, v0, v0 row_shr:4 row_mask:0xf bank_mask:0xf bound_ctrl:1
	v_add_f32_dpp v1, v1, v1 row_shr:4 row_mask:0xf bank_mask:0xf bound_ctrl:1
	v_add_f32_dpp v2, v2, v2 row_shr:4 row_mask:0xf bank_mask:0xf bound_ctrl:1
	v_add_f32_dpp v3, v3, v3 row_shr:4 row_mask:0xf bank_mask:0xf bound_ctrl:1
	v_add_f32_dpp v4, v4, v4 row_shr:4 row_mask:0xf bank_mask:0xf bound_ctrl:1
	v_add_f32_dpp v5, v5, v5 row_shr:4 row_mask:0xf bank_mask:0xf bound_ctrl:1
	v_add_f32_dpp v6, v6, v6 row_shr:4 row_mask:0xf bank_mask:0xf bound_ctrl:1
	v_add_f32_dpp v7, v7, v7 row_shr:4 row_mask:0xf bank_mask:0xf bound_ctrl:1
	v_add_f32_dpp v8, v8, v8 row_shr:4 row_mask:0xf bank_mask:0xf bound_ctrl:1
	v_add_f32_dpp v9, v9, v9 row_shr:4 row_mask:0xf bank_mask:0xf bound_ctrl:1
	v_add_f32_dpp v10, v10, v10 row_shr:4 row_mask:0xf bank_mask:0xf bound_ctrl:1
	v_add_f32_dpp v11, v11, v11 row_shr:4 row_mask:0xf bank_mask:0xf bound_ctrl:1
	v_add_f32_dpp v14, v14, v14 row_shr:4 row_mask:0xf bank_mask:0xf bound_ctrl:1
	v_add_f32_dpp v15, v15, v15 row_shr:4 row_mask:0xf bank_mask:0xf bound_ctrl:1
	v_add_f32_dpp v114, v114, v114 row_shr:4 row_mask:0xf bank_mask:0xf bound_ctrl:1
	v_add_f32_dpp v115, v115, v115 row_shr:4 row_mask:0xf bank_mask:0xf bound_ctrl:1
	v_add_f32_dpp v0, v0, v0 row_shr:8 row_mask:0xf bank_mask:0xf bound_ctrl:1
	v_add_f32_dpp v1, v1, v1 row_shr:8 row_mask:0xf bank_mask:0xf bound_ctrl:1
	v_add_f32_dpp v2, v2, v2 row_shr:8 row_mask:0xf bank_mask:0xf bound_ctrl:1
	v_add_f32_dpp v3, v3, v3 row_shr:8 row_mask:0xf bank_mask:0xf bound_ctrl:1
	v_add_f32_dpp v4, v4, v4 row_shr:8 row_mask:0xf bank_mask:0xf bound_ctrl:1
	v_add_f32_dpp v5, v5, v5 row_shr:8 row_mask:0xf bank_mask:0xf bound_ctrl:1
	v_add_f32_dpp v6, v6, v6 row_shr:8 row_mask:0xf bank_mask:0xf bound_ctrl:1
	v_add_f32_dpp v7, v7, v7 row_shr:8 row_mask:0xf bank_mask:0xf bound_ctrl:1
	v_add_f32_dpp v8, v8, v8 row_shr:8 row_mask:0xf bank_mask:0xf bound_ctrl:1
	v_add_f32_dpp v9, v9, v9 row_shr:8 row_mask:0xf bank_mask:0xf bound_ctrl:1
	v_add_f32_dpp v10, v10, v10 row_shr:8 row_mask:0xf bank_mask:0xf bound_ctrl:1
	v_add_f32_dpp v11, v11, v11 row_shr:8 row_mask:0xf bank_mask:0xf bound_ctrl:1
	v_add_f32_dpp v14, v14, v14 row_shr:8 row_mask:0xf bank_mask:0xf bound_ctrl:1
	v_add_f32_dpp v15, v15, v15 row_shr:8 row_mask:0xf bank_mask:0xf bound_ctrl:1
	v_add_f32_dpp v114, v114, v114 row_shr:8 row_mask:0xf bank_mask:0xf bound_ctrl:1
	v_add_f32_dpp v115, v115, v115 row_shr:8 row_mask:0xf bank_mask:0xf bound_ctrl:1
	v_add_f32_dpp v0, v0, v0 row_bcast:15 row_mask:0xa bank_mask:0xf
	v_add_f32_dpp v1, v1, v1 row_bcast:15 row_mask:0xa bank_mask:0xf
	v_add_f32_dpp v2, v2, v2 row_bcast:15 row_mask:0xa bank_mask:0xf
; DI unsigned cvtpk(float lo, float hi) { f32x2_t v = {lo, hi}; bf16x2_t b = __builtin_convertvector(v, bf16x2_t); return __builtin_bit_cast(unsigned, b); }
; DI float bflo(unsigned u) { return __uint_as_float(u << 16); }
; DI float bfhi(unsigned u) { return __uint_as_float(u & 0xffff0000u); }
; DI void phase_gla3(ArgsP a, int tb_, int l, bool with_ctx, char* shm, int vcu, int G) {
;     ...
;               for (int i = 0; i < 16; ++i) { const int kd = (wid & 3) * 16 + i, jj = dir ? 63 - lane : lane; const float x = scan64(LA[dir * 4160 + jj * 65 + kd], lane); LA[dir * 4160 + jj * 65 + kd] = x; } }
;             __syncthreads();
;             { const float qv[8] = {bflo(qw.x), bfhi(qw.x), bflo(qw.y), bfhi(qw.y), bflo(qw.z), bfhi(qw.z), bflo(qw.w), bfhi(qw.w)};
;               const float kv[8] = {bflo(kw.x), bfhi(kw.x), bflo(kw.y), bfhi(kw.y), bflo(kw.z), bfhi(kw.z), bflo(kw.w), bfhi(kw.w)};
; #pragma unroll
;               for (int dir = 0; dir < 2; ++dir) { float qt[8], kt[8];
; #pragma unroll
;                   for (int kk = 0; kk < 8; ++kk) { const float e = LA[dir * 4160 + j * 65 + kg * 8 + kk]; qt[kk] = qv[kk] * 0.125f * __expf(e); kt[kk] = kv[kk] * __expf(-e); }
;                   u32x4 w; w.x = cvtpk(qt[0], qt[1]); w.y = cvtpk(qt[2], qt[3]); w.z = cvtpk(qt[4], qt[5]); w.w = cvtpk(qt[6], qt[7]); *(u32x4*)(QT + dir * 9216 + j * 144 + kg * 16) = w;
;                   u32x4 w2; w2.x = cvtpk(kt[0], kt[1]); w2.y = cvtpk(kt[2], kt[3]); w2.z = cvtpk(kt[4], kt[5]); w2.w = cvtpk(kt[6], kt[7]); *(u32x4*)(KTt + dir * 9216 + j * 144 + kg * 16) = w2; }
	v_add_f32_dpp v3, v3, v3 row_bcast:15 row_mask:0xa bank_mask:0xf
	v_add_f32_dpp v4, v4, v4 row_bcast:15 row_mask:0xa bank_mask:0xf
	v_add_f32_dpp v5, v5, v5 row_bcast:15 row_mask:0xa bank_mask:0xf
	v_add_f32_dpp v6, v6, v6 row_bcast:15 row_mask:0xa bank_mask:0xf
	v_add_f32_dpp v7, v7, v7 row_bcast:15 row_mask:0xa bank_mask:0xf
	v_add_f32_dpp v8, v8, v8 row_bcast:15 row_mask:0xa bank_mask:0xf
	v_add_f32_dpp v9, v9, v9 row_bcast:15 row_mask:0xa bank_mask:0xf
	v_add_f32_dpp v10, v10, v10 row_bcast:15 row_mask:0xa bank_mask:0xf
	v_add_f32_dpp v11, v11, v11 row_bcast:15 row_mask:0xa bank_mask:0xf
	v_add_f32_dpp v14, v14, v14 row_bcast:15 row_mask:0xa bank_mask:0xf
	v_add_f32_dpp v15, v15, v15 row_bcast:15 row_mask:0xa bank_mask:0xf
	v_add_f32_dpp v114, v114, v114 row_bcast:15 row_mask:0xa bank_mask:0xf
	v_add_f32_dpp v115, v115, v115 row_bcast:15 row_mask:0xa bank_mask:0xf
	v_add_f32_dpp v0, v0, v0 row_bcast:31 row_mask:0xc bank_mask:0xf
	v_add_f32_dpp v1, v1, v1 row_bcast:31 row_mask:0xc bank_mask:0xf
	v_add_f32_dpp v2, v2, v2 row_bcast:31 row_mask:0xc bank_mask:0xf
	v_add_f32_dpp v3, v3, v3 row_bcast:31 row_mask:0xc bank_mask:0xf
	v_add_f32_dpp v4, v4, v4 row_bcast:31 row_mask:0xc bank_mask:0xf
	v_add_f32_dpp v5, v5, v5 row_bcast:31 row_mask:0xc bank_mask:0xf
	v_add_f32_dpp v6, v6, v6 row_bcast:31 row_mask:0xc bank_mask:0xf
	v_add_f32_dpp v7, v7, v7 row_bcast:31 row_mask:0xc bank_mask:0xf
	v_add_f32_dpp v8, v8, v8 row_bcast:31 row_mask:0xc bank_mask:0xf
	v_add_f32_dpp v9, v9, v9 row_bcast:31 row_mask:0xc bank_mask:0xf
	v_add_f32_dpp v10, v10, v10 row_bcast:31 row_mask:0xc bank_mask:0xf
	v_add_f32_dpp v11, v11, v11 row_bcast:31 row_mask:0xc bank_mask:0xf
	v_add_f32_dpp v14, v14, v14 row_bcast:31 row_mask:0xc bank_mask:0xf
	v_add_f32_dpp v15, v15, v15 row_bcast:31 row_mask:0xc bank_mask:0xf
	v_add_f32_dpp v114, v114, v114 row_bcast:31 row_mask:0xc bank_mask:0xf
	v_add_f32_dpp v115, v115, v115 row_bcast:31 row_mask:0xc bank_mask:0xf
	ds_write2_b32 v67, v0, v1 offset1:1
	ds_write2_b32 v67, v2, v3 offset0:2 offset1:3
	ds_write2_b32 v67, v4, v5 offset0:4 offset1:5
	ds_write2_b32 v67, v6, v7 offset0:6 offset1:7
	ds_write2_b32 v67, v8, v9 offset0:8 offset1:9
	ds_write2_b32 v67, v10, v11 offset0:10 offset1:11
	ds_write2_b32 v67, v14, v15 offset0:12 offset1:13
	ds_write2_b32 v67, v114, v115 offset0:14 offset1:15
	v_lshlrev_b32_e32 v12, 16, v48
	s_waitcnt lgkmcnt(0)
	s_barrier
	ds_read2_b32 v[0:1], v100 offset1:1
	ds_read2_b32 v[2:3], v100 offset0:2 offset1:3
	ds_read2_b32 v[4:5], v100 offset0:4 offset1:5
	ds_read2_b32 v[6:7], v100 offset0:6 offset1:7
	v_and_b32_e32 v13, 0xffff0000, v48
	v_lshlrev_b32_e32 v10, 16, v52
	v_and_b32_e32 v11, 0xffff0000, v52
	s_waitcnt lgkmcnt(3)
	v_mul_f32_e32 v8, 0x3fb8aa3b, v0
	v_mul_f32_e32 v0, 0xbfb8aa3b, v0
	v_mul_f32_e32 v9, 0x3fb8aa3b, v1
	v_mul_f32_e32 v1, 0xbfb8aa3b, v1
	v_exp_f32_e32 v0, v0
	v_exp_f32_e32 v1, v1
	v_lshlrev_b32_e32 v52, 16, v53
	v_and_b32_e32 v53, 0xffff0000, v53
	v_pk_mul_f32 v[52:53], v[52:53], s[90:91] op_sel_hi:[1,0]
	v_pk_mul_f32 v[14:15], v[0:1], v[12:13]
	s_waitcnt lgkmcnt(2)
	v_mul_f32_e32 v1, 0xbfb8aa3b, v2
	v_mul_f32_e32 v0, 0x3fb8aa3b, v2
	v_exp_f32_e32 v2, v1
	v_mul_f32_e32 v1, 0x3fb8aa3b, v3
	v_exp_f32_e32 v0, v0
	v_exp_f32_e32 v1, v1
	v_mul_f32_e32 v3, 0xbfb8aa3b, v3
	v_exp_f32_e32 v3, v3
	v_lshlrev_b32_e32 v48, 16, v49
	v_pk_mul_f32 v[114:115], v[52:53], v[0:1]
	v_and_b32_e32 v49, 0xffff0000, v49
	s_waitcnt lgkmcnt(1)
	v_mul_f32_e32 v1, 0xbfb8aa3b, v4
	v_pk_mul_f32 v[116:117], v[2:3], v[48:49]
	v_mul_f32_e32 v0, 0x3fb8aa3b, v4
	v_exp_f32_e32 v2, v1
	v_mul_f32_e32 v1, 0x3fb8aa3b, v5
	v_exp_f32_e32 v0, v0
	v_exp_f32_e32 v1, v1
	v_mul_f32_e32 v3, 0xbfb8aa3b, v5
	v_exp_f32_e32 v3, v3
	v_exp_f32_e32 v8, v8
	v_pk_mul_f32 v[4:5], v[118:119], v[0:1]
	s_waitcnt lgkmcnt(0)
	v_mul_f32_e32 v1, 0xbfb8aa3b, v6
	v_pk_mul_f32 v[122:123], v[2:3], v[120:121]
	v_mul_f32_e32 v0, 0x3fb8aa3b, v6
	v_exp_f32_e32 v2, v1
	v_mul_f32_e32 v1, 0x3fb8aa3b, v7
	v_exp_f32_e32 v9, v9
	v_exp_f32_e32 v0, v0
	v_exp_f32_e32 v1, v1
	v_mul_f32_e32 v3, 0xbfb8aa3b, v7
	v_exp_f32_e32 v3, v3
	v_pk_mul_f32 v[10:11], v[10:11], s[90:91] op_sel_hi:[1,0]
	v_pk_mul_f32 v[6:7], v[54:55], v[0:1]
	v_pk_mul_f32 v[8:9], v[10:11], v[8:9]
	v_pk_mul_f32 v[124:125], v[2:3], v[50:51]
	v_cvt_pk_bf16_f32 v0, v8, v9
	v_cvt_pk_bf16_f32 v1, v114, v115
	v_cvt_pk_bf16_f32 v2, v4, v5
	v_cvt_pk_bf16_f32 v3, v6, v7
	ds_write_b128 v101, v[0:3] offset:33792
	v_cvt_pk_bf16_f32 v0, v14, v15
	v_cvt_pk_bf16_f32 v1, v116, v117
	v_cvt_pk_bf16_f32 v2, v122, v123
	v_cvt_pk_bf16_f32 v3, v124, v125
	ds_write_b128 v101, v[0:3] offset:52224
	v_add_u32_e32 v0, 0x4100, v100
	ds_read2_b32 v[0:1], v0 offset1:1
	v_add_u32_e32 v2, 0x4108, v100
	v_add_u32_e32 v4, 0x4110, v100
	v_add_u32_e32 v6, 0x4118, v100
	ds_read2_b32 v[2:3], v2 offset1:1
	ds_read2_b32 v[4:5], v4 offset1:1
	ds_read2_b32 v[6:7], v6 offset1:1
	s_waitcnt lgkmcnt(3)
	v_mul_f32_e32 v8, 0x3fb8aa3b, v0
	v_mul_f32_e32 v0, 0xbfb8aa3b, v0
	v_mul_f32_e32 v9, 0x3fb8aa3b, v1
	v_mul_f32_e32 v1, 0xbfb8aa3b, v1
	v_exp_f32_e32 v8, v8
	v_exp_f32_e32 v0, v0
	v_exp_f32_e32 v9, v9
	v_exp_f32_e32 v1, v1
	s_waitcnt lgkmcnt(2)
	v_mul_f32_e32 v14, 0x3fb8aa3b, v2
	v_mul_f32_e32 v2, 0xbfb8aa3b, v2
	v_mul_f32_e32 v15, 0x3fb8aa3b, v3
	v_mul_f32_e32 v3, 0xbfb8aa3b, v3
	v_exp_f32_e32 v14, v14
	v_exp_f32_e32 v2, v2
	v_exp_f32_e32 v15, v15
	v_exp_f32_e32 v3, v3
	v_pk_mul_f32 v[8:9], v[10:11], v[8:9]
	v_pk_mul_f32 v[10:11], v[0:1], v[12:13]
	s_waitcnt lgkmcnt(1)
	v_mul_f32_e32 v1, 0xbfb8aa3b, v4
	v_pk_mul_f32 v[12:13], v[52:53], v[14:15]
	v_pk_mul_f32 v[14:15], v[2:3], v[48:49]
	v_exp_f32_e32 v2, v1
	v_mul_f32_e32 v1, 0x3fb8aa3b, v5
	v_mul_f32_e32 v3, 0xbfb8aa3b, v5
	s_waitcnt lgkmcnt(0)
; DI bf16_t f2bf(float f) { return (bf16_t)(cvtpk(f, f) & 0xffffu); }
; DI int crow(int r, int hi) { return (r & 3) + 8 * (r >> 2) + 4 * hi; }
; DI void phase_gla3(ArgsP a, int tb_, int l, bool with_ctx, char* shm, int vcu, int G) {
;     ...
;               const unsigned vv[8] = {v0.x, v0.y, v0.z, v0.w, v1.x, v1.y, v1.z, v1.w};
; #pragma unroll
;               for (int q = 0; q < 8; ++q) { *(bf16_t*)(VT + (kg * 16 + 2 * q) * 144 + j * 2) = (bf16_t)(vv[q] & 0xffffu); *(bf16_t*)(VT + (kg * 16 + 2 * q + 1) * 144 + j * 2) = (bf16_t)(vv[q] >> 16); } }
;             const u32x4* rp = (const u32x4*)(zr + (size_t)(m0 + j) * ZR + 1536 + h * 128 + kg * 16); const u32x4 r0 = rp[0], r1 = rp[1];
;             const int oib = wid >> 2, ovb = wid & 3;
;             bf16x8 sfr[2][4];
; #pragma unroll
;             for (int dir = 0; dir < 2; ++dir) { const bf16_t* sp = ST + ((size_t)((b * 4 + h) * 2 + dir) * NSLOT + (dir ? slot_b : slot_f)) * 8192 + (size_t)(ovb * 32 + r32) * 64 + 8 * hi;
; #pragma unroll
;                 for (int s4 = 0; s4 < 4; ++s4) sfr[dir][s4] = *(const bf16x8*)(sp + 16 * s4); }
;             __syncthreads();
;             { const int dir = wid >> 2, ib = (wid >> 1) & 1, jb = wid & 1; f32x16 acc;
; #pragma unroll
;               for (int r = 0; r < 16; ++r) acc[r] = 0.f;
; #pragma unroll
;               for (int s4 = 0; s4 < 4; ++s4) { const bf16x8 af = *(const bf16x8*)(QT + dir * 9216 + (ib * 32 + r32) * 144 + (16 * s4 + 8 * hi) * 2); const bf16x8 bfr = *(const bf16x8*)(KTt + dir * 9216 + (jb * 32 + r32) * 144 + (16 * s4 + 8 * hi) * 2);
;                   acc = __builtin_amdgcn_mfma_f32_32x32x16_bf16(af, bfr, acc, 0, 0, 0); }
;               const int jc = jb * 32 + r32;
; #pragma unroll
;               for (int r = 0; r < 16; ++r) { const int ir = ib * 32 + crow(r, hi); const bool keep = dir ? (jc >= ir) : (jc <= ir); *(bf16_t*)(AM + dir * 9216 + ir * 144 + jc * 2) = f2bf(keep ? acc[r] : 0.f); } }
;             __syncthreads();
	v_mul_f32_e32 v5, 0xbfb8aa3b, v6
	v_mul_f32_e32 v0, 0x3fb8aa3b, v4
	v_mul_f32_e32 v4, 0x3fb8aa3b, v6
	v_exp_f32_e32 v6, v5
	v_mul_f32_e32 v5, 0x3fb8aa3b, v7
	v_exp_f32_e32 v0, v0
	v_exp_f32_e32 v1, v1
	v_exp_f32_e32 v4, v4
	v_exp_f32_e32 v5, v5
	v_mul_f32_e32 v7, 0xbfb8aa3b, v7
	v_exp_f32_e32 v3, v3
	v_exp_f32_e32 v7, v7
	v_pk_mul_f32 v[48:49], v[118:119], v[0:1]
	v_pk_mul_f32 v[4:5], v[54:55], v[4:5]
	v_pk_mul_f32 v[52:53], v[2:3], v[120:121]
	v_pk_mul_f32 v[6:7], v[6:7], v[50:51]
	v_cvt_pk_bf16_f32 v0, v8, v9
	v_cvt_pk_bf16_f32 v1, v12, v13
	v_cvt_pk_bf16_f32 v2, v48, v49
	v_cvt_pk_bf16_f32 v3, v4, v5
	s_add_u32 s54, s33, s54
	ds_write_b128 v101, v[0:3] offset:43008
	v_cvt_pk_bf16_f32 v0, v10, v11
	v_cvt_pk_bf16_f32 v1, v14, v15
	v_cvt_pk_bf16_f32 v2, v52, v53
	v_cvt_pk_bf16_f32 v3, v6, v7
	v_add_u32_e32 v48, s55, v112
	s_addc_u32 s55, s2, 0
	ds_write_b128 v101, v[0:3] offset:61440
	ds_write_b16 v102, v44
	ds_write_b16_d16_hi v102, v44 offset:144
	ds_write_b16 v102, v45 offset:288
	ds_write_b16_d16_hi v102, v45 offset:432
	ds_write_b16 v102, v46 offset:576
	ds_write_b16_d16_hi v102, v46 offset:720
	ds_write_b16 v102, v47 offset:864
	ds_write_b16_d16_hi v102, v47 offset:1008
	ds_write_b16 v102, v40 offset:1152
	ds_write_b16_d16_hi v102, v40 offset:1296
	ds_write_b16 v102, v41 offset:1440
	ds_write_b16_d16_hi v102, v41 offset:1584
	ds_write_b16 v102, v42 offset:1728
	ds_write_b16_d16_hi v102, v42 offset:1872
	ds_write_b16 v102, v43 offset:2016
	ds_write_b16_d16_hi v102, v43 offset:2160
	v_mad_i64_i32 v[0:1], vcc, v48, s67, v[86:87]
	s_lshl_b64 s[54:55], s[54:55], 14
	global_load_dwordx4 v[40:43], v[0:1], off offset:3088
	global_load_dwordx4 v[44:47], v[0:1], off offset:3072
	global_load_dwordx4 v[50:53], v[82:83], off offset:-64
	global_load_dwordx4 v[114:117], v[82:83], off offset:-32
	global_load_dwordx4 v[118:121], v[82:83], off
	global_load_dwordx4 v[122:125], v[82:83], off offset:32
	v_lshl_add_u64 v[0:1], v[70:71], 0, s[54:55]
	global_load_dwordx4 v[126:129], v[0:1], off
	global_load_dwordx4 v[130:133], v[0:1], off offset:32
	global_load_dwordx4 v[134:137], v[0:1], off offset:64
	global_load_dwordx4 v[138:141], v[0:1], off offset:96
	s_waitcnt lgkmcnt(0)
	s_barrier
	ds_read_b128 v[0:3], v103 offset:33792
	ds_read_b128 v[4:7], v104 offset:52224
	s_waitcnt lgkmcnt(0)
	v_mfma_f32_32x32x16_bf16 v[0:15], v[0:3], v[4:7], 0
	ds_read_b128 v[142:145], v103 offset:33824
	ds_read_b128 v[146:149], v104 offset:52256
	s_add_u32 s33, s33, -8
	v_lshl_add_u64 v[82:83], v[82:83], 0, s[88:89]
	v_add_u32_e32 v112, 0x200, v112
	s_addc_u32 s2, s2, -1
	s_waitcnt lgkmcnt(0)
	v_mfma_f32_32x32x16_bf16 v[0:15], v[142:145], v[146:149], v[0:15]
	ds_read_b128 v[142:145], v103 offset:33856
	ds_read_b128 v[146:149], v104 offset:52288
	s_waitcnt lgkmcnt(0)
	v_mfma_f32_32x32x16_bf16 v[0:15], v[142:145], v[146:149], v[0:15]
	ds_read_b128 v[142:145], v103 offset:33888
	ds_read_b128 v[146:149], v104 offset:52320
	s_waitcnt lgkmcnt(0)
	v_mfma_f32_32x32x16_bf16 v[0:15], v[142:145], v[146:149], v[0:15]
	s_nop 11
	v_cvt_pk_bf16_f32 v0, v0, s0
	v_cndmask_b32_e64 v0, 0, v0, s[18:19]
	ds_write_b16 v105, v0
	v_cvt_pk_bf16_f32 v0, v1, s0
	v_cndmask_b32_e64 v0, 0, v0, s[20:21]
	ds_write_b16 v105, v0 offset:144
	v_cvt_pk_bf16_f32 v0, v2, s0
	v_cndmask_b32_e64 v0, 0, v0, s[22:23]
	ds_write_b16 v105, v0 offset:288
	v_cvt_pk_bf16_f32 v0, v3, s0
	v_cndmask_b32_e64 v0, 0, v0, s[24:25]
	ds_write_b16 v105, v0 offset:432
	v_cvt_pk_bf16_f32 v0, v4, s0
	v_cndmask_b32_e64 v0, 0, v0, s[26:27]
	ds_write_b16 v105, v0 offset:1152
	v_cvt_pk_bf16_f32 v0, v5, s0
	v_cndmask_b32_e64 v0, 0, v0, s[28:29]
	ds_write_b16 v105, v0 offset:1296
	v_cvt_pk_bf16_f32 v0, v6, s0
	v_cndmask_b32_e64 v0, 0, v0, s[30:31]
	ds_write_b16 v105, v0 offset:1440
	v_cvt_pk_bf16_f32 v0, v7, s0
	v_cndmask_b32_e64 v0, 0, v0, s[34:35]
	ds_write_b16 v105, v0 offset:1584
	v_cvt_pk_bf16_f32 v0, v8, s0
	v_cndmask_b32_e64 v0, 0, v0, s[36:37]
	ds_write_b16 v105, v0 offset:2304
	v_cvt_pk_bf16_f32 v0, v9, s0
	v_cndmask_b32_e64 v0, 0, v0, s[38:39]
	ds_write_b16 v105, v0 offset:2448
	v_cvt_pk_bf16_f32 v0, v10, s0
	v_cndmask_b32_e64 v0, 0, v0, s[40:41]
	ds_write_b16 v105, v0 offset:2592
	v_cvt_pk_bf16_f32 v0, v11, s0
	v_cndmask_b32_e64 v0, 0, v0, s[42:43]
	ds_write_b16 v105, v0 offset:2736
	v_cvt_pk_bf16_f32 v0, v12, s0
	v_cndmask_b32_e64 v0, 0, v0, s[44:45]
	ds_write_b16 v105, v0 offset:3456
	v_cvt_pk_bf16_f32 v0, v13, s0
	v_cndmask_b32_e64 v0, 0, v0, s[46:47]
	ds_write_b16 v105, v0 offset:3600
	v_cvt_pk_bf16_f32 v0, v14, s0
	v_cndmask_b32_e64 v0, 0, v0, s[48:49]
	ds_write_b16 v105, v0 offset:3744
	v_cvt_pk_bf16_f32 v0, v15, s0
	v_cndmask_b32_e64 v0, 0, v0, s[50:51]
	ds_write_b16 v105, v0 offset:3888
	s_waitcnt lgkmcnt(0)
	s_barrier
; DI int crow(int r, int hi) { return (r & 3) + 8 * (r >> 2) + 4 * hi; }
; DI void phase_gla3(ArgsP a, int tb_, int l, bool with_ctx, char* shm, int vcu, int G) {
;     ...
;             { f32x16 acc;
; #pragma unroll
;               for (int r = 0; r < 16; ++r) acc[r] = 0.f;
; #pragma unroll
;               for (int dir = 0; dir < 2; ++dir) {
; #pragma unroll
;                   for (int s4 = 0; s4 < 4; ++s4) { const bf16x8 af = *(const bf16x8*)(AM + dir * 9216 + (oib * 32 + r32) * 144 + (16 * s4 + 8 * hi) * 2); const bf16x8 bfr = *(const bf16x8*)(VT + (ovb * 32 + r32) * 144 + (16 * s4 + 8 * hi) * 2);
;                       acc = __builtin_amdgcn_mfma_f32_32x32x16_bf16(af, bfr, acc, 0, 0, 0); }
; #pragma unroll
;                   for (int s4 = 0; s4 < 4; ++s4) { const bf16x8 af = *(const bf16x8*)(QT + dir * 9216 + (oib * 32 + r32) * 144 + (16 * s4 + 8 * hi) * 2);
;                       acc = __builtin_amdgcn_mfma_f32_32x32x16_bf16(af, sfr[dir][s4], acc, 0, 0, 0); } }
; #pragma unroll
;               for (int r = 0; r < 16; ++r) OS[(oib * 32 + crow(r, hi)) * 132 + ovb * 32 + r32] = acc[r]; }
;             __syncthreads();
	ds_read_b128 v[0:3], v106
	ds_read_b128 v[142:145], v107
	s_waitcnt lgkmcnt(0)
	v_mfma_f32_32x32x16_bf16 v[0:15], v[0:3], v[142:145], 0
	ds_read_b128 v[146:149], v106 offset:32
	ds_read_b128 v[150:153], v107 offset:32
	s_waitcnt lgkmcnt(0)
	v_mfma_f32_32x32x16_bf16 v[0:15], v[146:149], v[150:153], v[0:15]
	ds_read_b128 v[146:149], v106 offset:64
	ds_read_b128 v[154:157], v107 offset:64
	s_waitcnt lgkmcnt(0)
	v_mfma_f32_32x32x16_bf16 v[0:15], v[146:149], v[154:157], v[0:15]
	ds_read_b128 v[146:149], v106 offset:96
	ds_read_b128 v[158:161], v107 offset:96
	s_waitcnt lgkmcnt(0)
	v_mfma_f32_32x32x16_bf16 v[0:15], v[146:149], v[158:161], v[0:15]
	ds_read_b128 v[146:149], v108 offset:33792
	s_waitcnt vmcnt(7) lgkmcnt(0)
	v_mfma_f32_32x32x16_bf16 v[0:15], v[146:149], v[50:53], v[0:15]
	ds_read_b128 v[50:53], v108 offset:33824
	s_waitcnt vmcnt(6) lgkmcnt(0)
	v_mfma_f32_32x32x16_bf16 v[0:15], v[50:53], v[114:117], v[0:15]
	ds_read_b128 v[50:53], v108 offset:33856
	s_waitcnt vmcnt(5) lgkmcnt(0)
	v_mfma_f32_32x32x16_bf16 v[0:15], v[50:53], v[118:121], v[0:15]
	ds_read_b128 v[50:53], v108 offset:33888
	s_waitcnt vmcnt(4) lgkmcnt(0)
	v_mfma_f32_32x32x16_bf16 v[0:15], v[50:53], v[122:125], v[0:15]
	ds_read_b128 v[50:53], v106 offset:9216
	s_waitcnt lgkmcnt(0)
	v_mfma_f32_32x32x16_bf16 v[0:15], v[50:53], v[142:145], v[0:15]
	ds_read_b128 v[50:53], v106 offset:9248
	s_waitcnt lgkmcnt(0)
	v_mfma_f32_32x32x16_bf16 v[0:15], v[50:53], v[150:153], v[0:15]
	ds_read_b128 v[50:53], v106 offset:9280
	s_waitcnt lgkmcnt(0)
	v_mfma_f32_32x32x16_bf16 v[0:15], v[50:53], v[154:157], v[0:15]
	ds_read_b128 v[50:53], v106 offset:9312
	s_waitcnt lgkmcnt(0)
	v_mfma_f32_32x32x16_bf16 v[0:15], v[50:53], v[158:161], v[0:15]
	ds_read_b128 v[50:53], v108 offset:43008
	s_waitcnt vmcnt(3) lgkmcnt(0)
	v_mfma_f32_32x32x16_bf16 v[0:15], v[50:53], v[126:129], v[0:15]
	ds_read_b128 v[50:53], v108 offset:43040
	s_waitcnt vmcnt(2) lgkmcnt(0)
	v_mfma_f32_32x32x16_bf16 v[0:15], v[50:53], v[130:133], v[0:15]
	ds_read_b128 v[50:53], v108 offset:43072
	s_waitcnt vmcnt(1) lgkmcnt(0)
	v_mfma_f32_32x32x16_bf16 v[0:15], v[50:53], v[134:137], v[0:15]
	ds_read_b128 v[50:53], v108 offset:43104
	s_waitcnt vmcnt(0) lgkmcnt(0)
	v_mfma_f32_32x32x16_bf16 v[0:15], v[50:53], v[138:141], v[0:15]
	s_nop 11
	ds_write2_b32 v109, v0, v1 offset1:132
	v_add_u32_e32 v0, 0x400, v109
	ds_write2_b32 v0, v2, v3 offset0:8 offset1:140
	v_add_u32_e32 v0, 0x1000, v109
	ds_write2_b32 v0, v4, v5 offset0:32 offset1:164
	v_add_u32_e32 v0, 0x1400, v109
	ds_write2_b32 v0, v6, v7 offset0:40 offset1:172
	v_add_u32_e32 v0, 0x2000, v109
	ds_write2_b32 v0, v8, v9 offset0:64 offset1:196
	v_add_u32_e32 v0, 0x2400, v109
	ds_write2_b32 v0, v10, v11 offset0:72 offset1:204
	v_add_u32_e32 v0, 0x3000, v109
	ds_write2_b32 v0, v12, v13 offset0:96 offset1:228
	v_add_u32_e32 v0, 0x3400, v109
	ds_write2_b32 v0, v14, v15 offset0:104 offset1:236
	s_waitcnt lgkmcnt(0)
	s_barrier
; DI unsigned cvtpk(float lo, float hi) { f32x2_t v = {lo, hi}; bf16x2_t b = __builtin_convertvector(v, bf16x2_t); return __builtin_bit_cast(unsigned, b); }
; DI float bflo(unsigned u) { return __uint_as_float(u << 16); }
; DI float bfhi(unsigned u) { return __uint_as_float(u & 0xffff0000u); }
; DI float shx(float v, int mask, int lane) { return __int_as_float(__builtin_amdgcn_ds_bpermute((lane ^ mask) << 2, __float_as_int(v))); }
; DI float silu_f(float x) { return x * sigm_f(x); }
; DI void phase_gla3(ArgsP a, int tb_, int l, bool with_ctx, char* shm, int vcu, int G) {
;     ...
;             { const int i = j, vg = kg; float o[16]; float ss = 0.f;
; #pragma unroll
;               for (int q = 0; q < 4; ++q) { const f32x4 t4 = *(const f32x4*)(OS + i * 132 + vg * 16 + 4 * q); o[4 * q] = t4.x; o[4 * q + 1] = t4.y; o[4 * q + 2] = t4.z; o[4 * q + 3] = t4.w; ss += (t4.x * t4.x + t4.y * t4.y) + (t4.z * t4.z + t4.w * t4.w); }
;               ss += shx(ss, 1, lane); ss += shx(ss, 2, lane); ss += shx(ss, 4, lane);
;               const float rn = rsqrtf(ss * (1.f / 128.f) + EPS);
;               const float gr[16] = {bflo(r0.x), bfhi(r0.x), bflo(r0.y), bfhi(r0.y), bflo(r0.z), bfhi(r0.z), bflo(r0.w), bfhi(r0.w), bflo(r1.x), bfhi(r1.x), bflo(r1.y), bfhi(r1.y), bflo(r1.z), bfhi(r1.z), bflo(r1.w), bfhi(r1.w)};
;               float y[16];
; #pragma unroll
;               for (int q = 0; q < 16; ++q) y[q] = o[q] * rn * ggl[vg * 16 + q] * silu_f(gr[q]);
;               u32x4 w0, w1; w0.x = cvtpk(y[0], y[1]); w0.y = cvtpk(y[2], y[3]); w0.z = cvtpk(y[4], y[5]); w0.w = cvtpk(y[6], y[7]); w1.x = cvtpk(y[8], y[9]); w1.y = cvtpk(y[10], y[11]); w1.z = cvtpk(y[12], y[13]); w1.w = cvtpk(y[14], y[15]);
;               u32x4* op = (u32x4*)(og + (size_t)(m0 + i) * 512 + h * 128 + vg * 16); op[0] = w0; op[1] = w1; }
;             __syncthreads();
	global_load_dwordx4 v[0:3], v[72:73], off
	global_load_dwordx4 v[8:11], v[72:73], off offset:16
	ds_read_b128 v[4:7], v110
	ds_read_b128 v[12:15], v110 offset:16
	ds_read_b128 v[50:53], v110 offset:32
	ds_read_b128 v[114:117], v110 offset:48
	s_waitcnt lgkmcnt(3)
	v_pk_mul_f32 v[54:55], v[6:7], v[6:7]
	v_pk_mul_f32 v[118:119], v[4:5], v[4:5]
	s_waitcnt lgkmcnt(0)
	v_mul_f32_e32 v49, v114, v114
	v_pk_mov_b32 v[120:121], v[118:119], v[54:55] op_sel:[1,0]
	v_mov_b32_e32 v119, v55
	v_pk_add_f32 v[54:55], v[120:121], v[118:119]
	v_pk_mul_f32 v[118:119], v[14:15], v[14:15]
	v_pk_mul_f32 v[120:121], v[12:13], v[12:13]
	v_mul_f32_e32 v79, v115, v115
	v_pk_mov_b32 v[122:123], v[120:121], v[118:119] op_sel:[1,0]
	v_mov_b32_e32 v121, v119
	v_pk_add_f32 v[118:119], v[122:123], v[120:121]
	v_pk_add_f32 v[54:55], v[54:55], v[54:55] op_sel:[0,1] op_sel_hi:[1,0]
	v_pk_add_f32 v[118:119], v[118:119], v[118:119] op_sel:[0,1] op_sel_hi:[1,0]
	v_mov_b32_e32 v55, v49
	v_mov_b32_e32 v119, v79
	v_pk_add_f32 v[54:55], v[54:55], v[118:119]
	v_mul_f32_e32 v118, v51, v51
	v_mul_f32_e32 v120, v53, v53
	v_mul_f32_e32 v81, v116, v116
	v_mul_f32_e32 v122, v117, v117
	v_pk_fma_f32 v[118:119], v[50:51], v[50:51], v[118:119] op_sel_hi:[1,1,0]
	v_pk_fma_f32 v[120:121], v[52:53], v[52:53], v[120:121] op_sel_hi:[1,1,0]
	v_mov_b32_e32 v119, v81
	v_mov_b32_e32 v121, v122
	v_pk_add_f32 v[118:119], v[118:119], v[120:121]
	global_load_dwordx4 v[122:125], v[72:73], off offset:48
	v_pk_add_f32 v[54:55], v[54:55], v[118:119]
	global_load_dwordx4 v[118:121], v[72:73], off offset:32
	v_add_f32_e32 v49, v54, v55
	ds_bpermute_b32 v54, v94, v49
	s_waitcnt lgkmcnt(0)
	v_add_f32_e32 v49, v49, v54
	ds_bpermute_b32 v54, v95, v49
	s_waitcnt lgkmcnt(0)
	v_add_f32_e32 v54, v49, v54
	ds_bpermute_b32 v55, v96, v54
	v_ashrrev_i32_e32 v49, 31, v48
	s_waitcnt lgkmcnt(0)
	v_add_f32_e32 v54, v54, v55
	v_fmamk_f32 v54, v54, 0x3c000000, v230
	v_mul_f32_e32 v55, 0x4b800000, v54
	v_cmp_gt_f32_e32 vcc, s76, v54
	s_nop 1
	v_cndmask_b32_e32 v54, v54, v55, vcc
	v_rsq_f32_e32 v55, v54
	v_lshlrev_b32_e32 v54, 16, v44
	v_mul_f32_e32 v79, 0xbfb8aa3b, v54
	v_exp_f32_e32 v79, v79
	v_mul_f32_e32 v81, 0x45800000, v55
	v_cndmask_b32_e32 v126, v55, v81, vcc
	v_and_b32_e32 v55, 0xffff0000, v44
	v_add_f32_e32 v44, 1.0, v79
	v_mul_f32_e32 v79, 0xbfb8aa3b, v55
	v_exp_f32_e32 v79, v79
	v_pk_mul_f32 v[4:5], v[4:5], v[126:127] op_sel_hi:[1,0]
	v_rcp_f32_e32 v128, v44
	v_pk_mul_f32 v[6:7], v[6:7], v[126:127] op_sel_hi:[1,0]
	v_pk_mul_f32 v[12:13], v[12:13], v[126:127] op_sel_hi:[1,0]
	s_and_b64 vcc, exec, s[60:61]
	s_waitcnt vmcnt(3)
	v_pk_mul_f32 v[0:1], v[0:1], v[4:5]
	v_add_f32_e32 v4, 1.0, v79
	v_rcp_f32_e32 v129, v4
	v_lshlrev_b32_e32 v4, 16, v45
	v_mul_f32_e32 v5, 0xbfb8aa3b, v4
	v_exp_f32_e32 v44, v5
	v_and_b32_e32 v5, 0xffff0000, v45
	v_mul_f32_e32 v45, 0xbfb8aa3b, v5
	v_exp_f32_e32 v45, v45
	v_add_f32_e32 v44, 1.0, v44
	v_pk_mul_f32 v[2:3], v[2:3], v[6:7]
	v_rcp_f32_e32 v44, v44
	v_add_f32_e32 v6, 1.0, v45
	v_rcp_f32_e32 v45, v6
	v_lshlrev_b32_e32 v6, 16, v46
	v_pk_mul_f32 v[54:55], v[128:129], v[54:55]
	v_mul_f32_e32 v7, 0xbfb8aa3b, v6
	v_pk_mul_f32 v[0:1], v[54:55], v[0:1]
	v_exp_f32_e32 v54, v7
	v_pk_mul_f32 v[4:5], v[44:45], v[4:5]
	v_and_b32_e32 v7, 0xffff0000, v46
	v_pk_mul_f32 v[2:3], v[4:5], v[2:3]
	v_mul_f32_e32 v5, 0xbfb8aa3b, v7
	v_exp_f32_e32 v5, v5
	v_add_f32_e32 v4, 1.0, v54
	v_rcp_f32_e32 v4, v4
	s_waitcnt vmcnt(2)
	v_pk_mul_f32 v[8:9], v[8:9], v[12:13]
	v_add_f32_e32 v5, 1.0, v5
	v_rcp_f32_e32 v5, v5
	v_lshlrev_b32_e32 v12, 16, v47
	v_mul_f32_e32 v13, 0xbfb8aa3b, v12
	v_exp_f32_e32 v44, v13
	v_and_b32_e32 v13, 0xffff0000, v47
	v_pk_mul_f32 v[4:5], v[4:5], v[6:7]
	v_mul_f32_e32 v7, 0xbfb8aa3b, v13
	v_exp_f32_e32 v7, v7
	v_add_f32_e32 v6, 1.0, v44
	v_rcp_f32_e32 v6, v6
	v_pk_mul_f32 v[4:5], v[4:5], v[8:9]
	v_add_f32_e32 v7, 1.0, v7
	v_rcp_f32_e32 v7, v7
	v_pk_mul_f32 v[8:9], v[14:15], v[126:127] op_sel_hi:[1,0]
	v_cvt_pk_bf16_f32 v0, v0, v1
	v_pk_mul_f32 v[8:9], v[10:11], v[8:9]
	v_lshlrev_b32_e32 v10, 16, v40
	v_mul_f32_e32 v11, 0xbfb8aa3b, v10
	v_exp_f32_e32 v14, v11
	v_pk_mul_f32 v[6:7], v[6:7], v[12:13]
	v_and_b32_e32 v11, 0xffff0000, v40
	v_pk_mul_f32 v[6:7], v[6:7], v[8:9]
	v_mul_f32_e32 v9, 0xbfb8aa3b, v11
	v_exp_f32_e32 v9, v9
	v_add_f32_e32 v8, 1.0, v14
	v_rcp_f32_e32 v8, v8
	v_lshlrev_b32_e32 v14, 16, v41
	v_add_f32_e32 v9, 1.0, v9
	v_rcp_f32_e32 v9, v9
	v_mul_f32_e32 v15, 0xbfb8aa3b, v14
	v_exp_f32_e32 v40, v15
	v_and_b32_e32 v15, 0xffff0000, v41
	v_pk_mul_f32 v[8:9], v[8:9], v[10:11]
	v_mul_f32_e32 v11, 0xbfb8aa3b, v15
	v_exp_f32_e32 v11, v11
	v_add_f32_e32 v10, 1.0, v40
	v_lshlrev_b32_e32 v40, 16, v42
	v_and_b32_e32 v41, 0xffff0000, v42
	v_add_f32_e32 v11, 1.0, v11
	v_mul_f32_e32 v42, 0xbfb8aa3b, v40
	v_mul_f32_e32 v44, 0xbfb8aa3b, v41
	v_rcp_f32_e32 v10, v10
	v_rcp_f32_e32 v11, v11
	v_exp_f32_e32 v42, v42
	v_exp_f32_e32 v44, v44
	v_pk_mul_f32 v[12:13], v[50:51], v[126:127] op_sel_hi:[1,0]
	v_pk_mul_f32 v[10:11], v[10:11], v[14:15]
	v_add_f32_e32 v14, 1.0, v42
	v_add_f32_e32 v15, 1.0, v44
	s_waitcnt vmcnt(0)
	v_pk_mul_f32 v[12:13], v[118:119], v[12:13]
	v_rcp_f32_e32 v14, v14
	v_rcp_f32_e32 v15, v15
	v_pk_mul_f32 v[8:9], v[8:9], v[12:13]
	v_pk_mul_f32 v[12:13], v[52:53], v[126:127] op_sel_hi:[1,0]
	v_cvt_pk_bf16_f32 v1, v2, v3
	v_pk_mul_f32 v[12:13], v[120:121], v[12:13]
	v_pk_mul_f32 v[14:15], v[14:15], v[40:41]
	v_pk_mul_f32 v[10:11], v[10:11], v[12:13]
	v_pk_mul_f32 v[12:13], v[114:115], v[126:127] op_sel_hi:[1,0]
	v_cvt_pk_bf16_f32 v2, v4, v5
	v_pk_mul_f32 v[12:13], v[12:13], v[122:123]
	v_cvt_pk_bf16_f32 v4, v8, v9
	v_pk_mul_f32 v[12:13], v[14:15], v[12:13]
	v_lshlrev_b32_e32 v14, 16, v43
	v_mul_f32_e32 v15, 0xbfb8aa3b, v14
	v_exp_f32_e32 v40, v15
	v_and_b32_e32 v15, 0xffff0000, v43
	v_mul_f32_e32 v41, 0xbfb8aa3b, v15
	v_exp_f32_e32 v41, v41
	v_add_f32_e32 v40, 1.0, v40
	v_rcp_f32_e32 v40, v40
	v_pk_mul_f32 v[42:43], v[116:117], v[126:127] op_sel_hi:[1,0]
	v_add_f32_e32 v41, 1.0, v41
	v_rcp_f32_e32 v41, v41
	v_cvt_pk_bf16_f32 v5, v10, v11
	v_pk_mul_f32 v[10:11], v[42:43], v[124:125]
	v_cvt_pk_bf16_f32 v3, v6, v7
	v_pk_mul_f32 v[8:9], v[40:41], v[14:15]
	v_cvt_pk_bf16_f32 v6, v12, v13
	v_pk_mul_f32 v[8:9], v[8:9], v[10:11]
	v_mov_b64_e32 v[54:55], v[22:23]
	v_cvt_pk_bf16_f32 v7, v8, v9
	v_lshlrev_b64 v[8:9], 10, v[48:49]
	v_lshl_add_u64 v[8:9], v[84:85], 0, v[8:9]
	global_store_dwordx4 v[8:9], v[0:3], off
	global_store_dwordx4 v[8:9], v[4:7], off offset:16
	v_mov_b64_e32 v[50:51], v[38:39]
	v_mov_b64_e32 v[0:1], v[24:25]
	v_mov_b64_e32 v[46:47], v[34:35]
	v_mov_b64_e32 v[42:43], v[30:31]
	v_mov_b64_e32 v[2:3], v[26:27]
	v_mov_b64_e32 v[52:53], v[20:21]
	v_mov_b64_e32 v[48:49], v[36:37]
	v_mov_b64_e32 v[44:45], v[32:33]
	v_mov_b64_e32 v[40:41], v[28:29]
	s_barrier
	s_cbranch_vccnz .LBB0_1415
